# attention loop back edge rotated: loop-carried v_mov hoisted before the end-of-tile barrier, single taken branch after the barrier (exit falls through)
# speedup vs baseline: 1.0031x; 1.0009x over previous
; #define ATT_WRITE(buf) do { _Pragma("unroll") for (int i_ = 0; i_ < 3; ++i_) *(LAS u32x4*)(lds + OFF_K + (buf) * KBUF + kd[i_]) = kreg[i_]; \
;         _Pragma("unroll") for (int i_ = 0; i_ < 2; ++i_) { LAS u32x2* d_ = (LAS u32x2*)(lds + OFF_V + (buf) * VBUF + vd[i_]); d_[0] = (u32x2){vreg[i_].x, vreg[i_].y}; d_[2] = (u32x2){vreg[i_].z, vreg[i_].w}; } } while (0)
; __device__ __forceinline__ void unit(LAS unsigned char* lds, const Tensors& T, int h, int qrow0, int nact, bool sample, int limbase, int kv0, int kvnew, int nt) {
;     ...
;         if (t + 1 < nt) ATT_WRITE(buf ^ 1);
;         __syncthreads();
.LBB0_912:
	s_xor_b32 s0, s16, 1
	s_mul_i32 s1, s0, 0x6400
	s_add_i32 s1, s1, 0
	v_add_u32_e32 v64, s1, v219
	s_waitcnt vmcnt(4)
	ds_write_b128 v64, v[160:163]
	v_add_u32_e32 v64, s1, v218
	s_mulk_i32 s0, 0xe400
	s_waitcnt vmcnt(3)
	ds_write_b128 v64, v[156:159]
	v_add_u32_e32 v64, s1, v220
	s_add_i32 s1, s1, s0
	s_waitcnt vmcnt(2)
	ds_write_b128 v64, v[152:155]
	v_add_u32_e32 v64, s1, v188
	v_add_u32_e32 v64, 0xc800, v64
	s_add_i32 s9, s9, 1
	s_waitcnt vmcnt(1)
	ds_write2_b64 v64, v[148:149], v[150:151] offset1:2
	v_add_u32_e32 v64, s1, v190
	v_add_u32_e32 v64, 0xc800, v64
	v_lshl_add_u64 v[192:193], v[192:193], 0, v[164:165]
	v_lshl_add_u64 v[194:195], v[194:195], 0, v[196:197]
	v_lshl_add_u64 v[198:199], v[198:199], 0, v[200:201]
	v_lshl_add_u64 v[202:203], v[202:203], 0, s[14:15]
	s_cmp_eq_u32 s13, s9
	v_lshl_add_u64 v[204:205], v[204:205], 0, s[14:15]
	s_waitcnt vmcnt(0)
	ds_write2_b64 v64, v[144:145], v[146:147] offset1:2
	v_mov_b32_e32 v223, v222
	s_waitcnt lgkmcnt(0)
	s_barrier
	s_cbranch_scc0 .LBB0_904
